# sample item: cached-key score loads coalesced (4 rows x 256 B per load, DPP row reduce, scores via LDS)
# speedup vs baseline: 1.0161x; 1.0161x over previous
.LBB0_289:
	v_lshl_add_u64 v[22:23], v[20:21], 0, s[20:21]
	v_lshl_add_u64 v[34:35], v[18:19], 0, s[20:21]
	global_load_dword v36, v[22:23], off
	global_load_dword v38, v[22:23], off offset:256
	global_load_dword v40, v[22:23], off offset:512
	global_load_dword v42, v[22:23], off offset:768
	global_load_dword v44, v[22:23], off offset:1024
	global_load_dword v46, v[22:23], off offset:1280
	global_load_dword v48, v[22:23], off offset:1536
	global_load_dword v50, v[22:23], off offset:1792
	global_load_dword v37, v[34:35], off
	global_load_dword v39, v[34:35], off offset:256
	global_load_dword v41, v[34:35], off offset:512
	global_load_dword v43, v[34:35], off offset:768
	global_load_dword v45, v[34:35], off offset:1024
	global_load_dword v47, v[34:35], off offset:1280
	global_load_dword v49, v[34:35], off offset:1536
	global_load_dword v51, v[34:35], off offset:1792
	global_load_dword v52, v[22:23], off offset:2048
	global_load_dword v54, v[22:23], off offset:2304
	global_load_dword v56, v[22:23], off offset:2560
	global_load_dword v58, v[22:23], off offset:2816
	global_load_dword v60, v[22:23], off offset:3072
	global_load_dword v62, v[22:23], off offset:3328
	global_load_dword v64, v[22:23], off offset:3584
	global_load_dword v66, v[22:23], off offset:3840
	global_load_dword v53, v[34:35], off offset:2048
	global_load_dword v55, v[34:35], off offset:2304
	global_load_dword v57, v[34:35], off offset:2560
	global_load_dword v59, v[34:35], off offset:2816
	global_load_dword v61, v[34:35], off offset:3072
	global_load_dword v63, v[34:35], off offset:3328
	global_load_dword v65, v[34:35], off offset:3584
	global_load_dword v67, v[34:35], off offset:3840
	v_add_co_u32_e32 v22, vcc, s29, v22
	v_add_u32_e32 v11, 0xffffff84, v2
	s_nop 0
	v_addc_co_u32_e32 v23, vcc, 0, v23, vcc
	v_add_co_u32_e32 v34, vcc, s29, v34
	v_add_u32_e32 v99, 0xffffff88, v2
	s_nop 0
	v_addc_co_u32_e32 v35, vcc, 0, v35, vcc
	global_load_dword v68, v[22:23], off
	global_load_dword v70, v[22:23], off offset:256
	global_load_dword v72, v[22:23], off offset:512
	global_load_dword v74, v[22:23], off offset:768
	global_load_dword v76, v[22:23], off offset:1024
	global_load_dword v78, v[22:23], off offset:1280
	global_load_dword v80, v[22:23], off offset:1536
	global_load_dword v82, v[22:23], off offset:1792
	global_load_dword v69, v[34:35], off
	global_load_dword v71, v[34:35], off offset:256
	global_load_dword v73, v[34:35], off offset:512
	global_load_dword v75, v[34:35], off offset:768
	global_load_dword v77, v[34:35], off offset:1024
	global_load_dword v79, v[34:35], off offset:1280
	global_load_dword v81, v[34:35], off offset:1536
	global_load_dword v83, v[34:35], off offset:1792
	global_load_dword v84, v[22:23], off offset:2048
	global_load_dword v86, v[22:23], off offset:2304
	global_load_dword v88, v[22:23], off offset:2560
	global_load_dword v90, v[22:23], off offset:2816
	global_load_dword v92, v[22:23], off offset:3072
	global_load_dword v94, v[22:23], off offset:3328
	global_load_dword v96, v[22:23], off offset:3584
	s_nop 0
	global_load_dword v22, v[22:23], off offset:3840
	s_nop 0
	global_load_dword v85, v[34:35], off offset:2048
	global_load_dword v87, v[34:35], off offset:2304
	global_load_dword v89, v[34:35], off offset:2560
	global_load_dword v91, v[34:35], off offset:2816
	global_load_dword v93, v[34:35], off offset:3072
	global_load_dword v95, v[34:35], off offset:3328
	global_load_dword v97, v[34:35], off offset:3584
	global_load_dword v23, v[34:35], off offset:3840
	ds_bpermute_b32 v98, v11, v1
	v_add_u32_e32 v101, 0xffffff8c, v2
	ds_bpermute_b32 v100, v99, v1
	v_add_u32_e32 v103, 0xffffff90, v2
	ds_bpermute_b32 v102, v101, v1
	v_add_u32_e32 v105, 0xffffff94, v2
	ds_bpermute_b32 v104, v103, v1
	v_add_u32_e32 v107, 0xffffff98, v2
	ds_bpermute_b32 v106, v105, v1
	v_add_u32_e32 v109, 0xffffff9c, v2
	ds_bpermute_b32 v108, v107, v1
	v_add_u32_e32 v111, 0xffffffa0, v2
	ds_bpermute_b32 v110, v109, v1
	v_add_u32_e32 v113, 0xffffffa4, v2
	ds_bpermute_b32 v112, v111, v1
	v_add_u32_e32 v115, 0xffffffa8, v2
	ds_bpermute_b32 v114, v113, v1
	v_add_u32_e32 v117, 0xffffffac, v2
	ds_bpermute_b32 v116, v115, v1
	v_add_u32_e32 v119, 0xffffffb0, v2
	ds_bpermute_b32 v118, v117, v1
	v_add_u32_e32 v121, 0xffffffb4, v2
	ds_bpermute_b32 v120, v119, v1
	v_add_u32_e32 v123, 0xffffffb8, v2
	ds_bpermute_b32 v122, v121, v1
	v_add_u32_e32 v125, 0xffffffbc, v2
	ds_bpermute_b32 v124, v123, v1
	v_subrev_u32_e32 v127, 64, v2
	ds_bpermute_b32 v126, v125, v1
	v_subrev_u32_e32 v129, 60, v2
	ds_bpermute_b32 v128, v127, v1
	v_subrev_u32_e32 v131, 56, v2
	ds_bpermute_b32 v130, v129, v1
	v_subrev_u32_e32 v133, 52, v2
	ds_bpermute_b32 v132, v131, v1
	v_subrev_u32_e32 v35, 48, v2
	ds_bpermute_b32 v134, v133, v1
	v_subrev_u32_e32 v135, 44, v2
	ds_bpermute_b32 v136, v35, v1
	v_subrev_u32_e32 v137, 40, v2
	ds_bpermute_b32 v138, v135, v1
	v_subrev_u32_e32 v139, 36, v2
	ds_bpermute_b32 v140, v137, v1
	v_subrev_u32_e32 v141, 32, v2
	ds_bpermute_b32 v142, v139, v1
	s_waitcnt vmcnt(55) lgkmcnt(14)
	v_pk_fma_f32 v[16:17], v[36:37], v[98:99], v[16:17] op_sel_hi:[1,0,1]
	v_subrev_u32_e32 v143, 28, v2
	s_waitcnt vmcnt(54)
	v_pk_fma_f32 v[16:17], v[38:39], v[100:101], v[16:17] op_sel_hi:[1,0,1]
	ds_bpermute_b32 v146, v141, v1
	s_waitcnt vmcnt(53)
	v_pk_fma_f32 v[16:17], v[40:41], v[102:103], v[16:17] op_sel_hi:[1,0,1]
	v_subrev_u32_e32 v145, 24, v2
	s_waitcnt vmcnt(52)
	v_pk_fma_f32 v[16:17], v[42:43], v[104:105], v[16:17] op_sel_hi:[1,0,1]
	ds_bpermute_b32 v148, v143, v1
	s_waitcnt vmcnt(51)
	v_pk_fma_f32 v[16:17], v[44:45], v[106:107], v[16:17] op_sel_hi:[1,0,1]
	v_subrev_u32_e32 v147, 20, v2
	s_waitcnt vmcnt(50)
	v_pk_fma_f32 v[16:17], v[46:47], v[108:109], v[16:17] op_sel_hi:[1,0,1]
	ds_bpermute_b32 v150, v145, v1
	s_waitcnt vmcnt(49)
	v_pk_fma_f32 v[16:17], v[48:49], v[110:111], v[16:17] op_sel_hi:[1,0,1]
	v_add_u32_e32 v149, -16, v2
	s_waitcnt vmcnt(48)
	v_pk_fma_f32 v[16:17], v[50:51], v[112:113], v[16:17] op_sel_hi:[1,0,1]
	ds_bpermute_b32 v152, v147, v1
	s_waitcnt vmcnt(39)
	v_pk_fma_f32 v[16:17], v[52:53], v[114:115], v[16:17] op_sel_hi:[1,0,1]
	v_add_u32_e32 v151, -12, v2
	s_waitcnt vmcnt(38) lgkmcnt(14)
	v_pk_fma_f32 v[16:17], v[54:55], v[116:117], v[16:17] op_sel_hi:[1,0,1]
	ds_bpermute_b32 v154, v149, v1
	s_waitcnt vmcnt(37)
	v_pk_fma_f32 v[16:17], v[56:57], v[118:119], v[16:17] op_sel_hi:[1,0,1]
	v_add_u32_e32 v153, -8, v2
	s_waitcnt vmcnt(36)
	v_pk_fma_f32 v[16:17], v[58:59], v[120:121], v[16:17] op_sel_hi:[1,0,1]
	ds_bpermute_b32 v156, v151, v1
	s_waitcnt vmcnt(35)
	v_pk_fma_f32 v[16:17], v[60:61], v[122:123], v[16:17] op_sel_hi:[1,0,1]
	v_add_u32_e32 v155, -4, v2
	s_waitcnt vmcnt(34) lgkmcnt(14)
	v_pk_fma_f32 v[16:17], v[62:63], v[124:125], v[16:17] op_sel_hi:[1,0,1]
	ds_bpermute_b32 v158, v153, v1
	s_waitcnt vmcnt(33)
	v_pk_fma_f32 v[16:17], v[64:65], v[126:127], v[16:17] op_sel_hi:[1,0,1]
	ds_bpermute_b32 v160, v155, v1
	s_waitcnt vmcnt(32) lgkmcnt(14)
	v_pk_fma_f32 v[16:17], v[66:67], v[128:129], v[16:17] op_sel_hi:[1,0,1]
	ds_bpermute_b32 v34, v2, v1
	s_waitcnt vmcnt(23)
	v_pk_fma_f32 v[16:17], v[68:69], v[130:131], v[16:17] op_sel_hi:[1,0,1]
	s_add_u32 s20, s20, 0x2000
	s_waitcnt vmcnt(22) lgkmcnt(14)
	v_pk_fma_f32 v[16:17], v[70:71], v[132:133], v[16:17] op_sel_hi:[1,0,1]
	s_addc_u32 s21, s21, 0
	s_waitcnt vmcnt(21) lgkmcnt(13)
	v_pk_fma_f32 v[16:17], v[72:73], v[134:135], v[16:17] op_sel_hi:[1,0,1]
	v_add_u32_e32 v2, 0x80, v2
	s_waitcnt vmcnt(20) lgkmcnt(12)
	v_pk_fma_f32 v[16:17], v[74:75], v[136:137], v[16:17] op_sel_hi:[1,0,1]
	s_cmpk_eq_i32 s20, 0x4000
	s_waitcnt vmcnt(19) lgkmcnt(11)
	v_pk_fma_f32 v[16:17], v[76:77], v[138:139], v[16:17] op_sel_hi:[1,0,1]
	s_waitcnt vmcnt(18) lgkmcnt(10)
	v_pk_fma_f32 v[16:17], v[78:79], v[140:141], v[16:17] op_sel_hi:[1,0,1]
	s_waitcnt vmcnt(17) lgkmcnt(9)
	v_pk_fma_f32 v[16:17], v[80:81], v[142:143], v[16:17] op_sel_hi:[1,0,1]
	s_waitcnt vmcnt(16) lgkmcnt(8)
	v_pk_fma_f32 v[16:17], v[82:83], v[146:147], v[16:17] op_sel_hi:[1,0,1]
	s_waitcnt vmcnt(7) lgkmcnt(7)
	v_pk_fma_f32 v[16:17], v[84:85], v[148:149], v[16:17] op_sel_hi:[1,0,1]
	s_waitcnt vmcnt(6) lgkmcnt(6)
	v_pk_fma_f32 v[16:17], v[86:87], v[150:151], v[16:17] op_sel_hi:[1,0,1]
	s_waitcnt vmcnt(5) lgkmcnt(5)
	v_pk_fma_f32 v[16:17], v[88:89], v[152:153], v[16:17] op_sel_hi:[1,0,1]
	s_waitcnt vmcnt(4) lgkmcnt(4)
	v_pk_fma_f32 v[16:17], v[90:91], v[154:155], v[16:17] op_sel_hi:[1,0,1]
	s_waitcnt vmcnt(3) lgkmcnt(3)
	v_pk_fma_f32 v[16:17], v[92:93], v[156:157], v[16:17] op_sel_hi:[1,0,1]
	s_waitcnt vmcnt(2) lgkmcnt(2)
	v_pk_fma_f32 v[16:17], v[94:95], v[158:159], v[16:17] op_sel_hi:[1,0,1]
	s_waitcnt vmcnt(1) lgkmcnt(1)
	v_pk_fma_f32 v[16:17], v[96:97], v[160:161], v[16:17] op_sel_hi:[1,0,1]
	s_waitcnt vmcnt(0) lgkmcnt(0)
	v_pk_fma_f32 v[16:17], v[22:23], v[34:35], v[16:17] op_sel_hi:[1,0,1]
	s_cbranch_scc0 .LBB0_289
	v_readlane_b32 s84, v254, 23
	v_lshlrev_b32_e32 v2, 2, v12
	v_readlane_b32 s98, v254, 37
	v_readlane_b32 s99, v254, 38
	v_mul_f32_e32 v11, 0xbfb8aa3b, v16
	v_exp_f32_e32 v11, v11
	s_lshl_b32 s51, s51, 6
	v_readlane_b32 s52, v254, 7
	s_lshr_b32 s2, s50, 2
	global_load_dword v18, v2, s[98:99]
	s_lshl_b64 s[20:21], s[18:19], 12
	s_and_b32 s51, s51, 0x300
	v_readlane_b32 s62, v254, 17
	v_readlane_b32 s53, v254, 8
	v_readlane_b32 s63, v254, 18
	s_add_u32 s52, s62, s20
	v_mul_f32_e32 v19, 0xbfb8aa3b, v17
	v_lshlrev_b32_e32 v20, 1, v0
	s_addc_u32 s53, s63, s21
	v_add_f32_e32 v11, 1.0, v11
	v_exp_f32_e32 v21, v19
	v_lshl_or_b32 v19, s2, 7, v20
	global_load_dword v20, v2, s[52:53]
	v_rcp_f32_e32 v22, v11
	v_add_co_u32_e32 v16, vcc, s29, v14
	v_add_f32_e32 v21, 1.0, v21
	s_nop 0
	v_addc_co_u32_e32 v17, vcc, 0, v15, vcc
	v_mul_f32_e32 v22, 0xc1000000, v22
	v_rcp_f32_e32 v21, v21
	s_add_u32 s20, s80, s20
	s_addc_u32 s21, s81, s21
	s_lshl_b32 s18, s18, 7
	v_readlane_b32 s56, v254, 11
	v_readlane_b32 s57, v254, 12
	s_lshl_b32 s2, s2, 8
	v_mov_b32_e32 v126, s24
	v_readlane_b32 s85, v254, 24
	s_ashr_i32 s19, s18, 31
	v_readlane_b32 s86, v254, 25
	v_readlane_b32 s87, v254, 26
	v_readlane_b32 s88, v254, 27
	v_readlane_b32 s89, v254, 28
	v_readlane_b32 s90, v254, 29
	v_readlane_b32 s91, v254, 30
	v_readlane_b32 s92, v254, 31
	v_readlane_b32 s93, v254, 32
	v_readlane_b32 s94, v254, 33
	v_readlane_b32 s95, v254, 34
	v_readlane_b32 s96, v254, 35
	v_readlane_b32 s97, v254, 36
	v_readlane_b32 s54, v254, 9
	v_readlane_b32 s55, v254, 10
	v_readlane_b32 s58, v254, 13
	v_readlane_b32 s59, v254, 14
	v_readlane_b32 s60, v254, 15
	v_readlane_b32 s61, v254, 16
	v_readlane_b32 s64, v254, 19
	v_readlane_b32 s65, v254, 20
	v_readlane_b32 s66, v254, 21
	v_readlane_b32 s67, v254, 22
	s_waitcnt vmcnt(1)
	v_mul_f32_e32 v11, 0xbfb8aa3b, v18
	v_fma_f32 v23, v18, s33, -v11
	v_rndne_f32_e32 v34, v11
	v_fmac_f32_e32 v23, 0xb2a5705f, v18
	v_sub_f32_e32 v11, v11, v34
	v_add_f32_e32 v11, v11, v23
	v_cvt_i32_f32_e32 v34, v34
	v_exp_f32_e32 v23, v11
	global_load_ushort v11, v[16:17], off offset:1024
	global_load_ushort v35, v19, s[0:1] offset:2560
	global_load_ushort v80, v19, s[0:1] offset:2048
	global_load_ushort v36, v[14:15], off
	v_cmp_nlt_f32_e32 vcc, s34, v18
	v_ldexp_f32 v19, v23, v34
	s_nop 0
	v_cndmask_b32_e32 v19, 0, v19, vcc
	v_cmp_ngt_f32_e32 vcc, s35, v18
	s_nop 1
	v_cndmask_b32_e32 v23, v33, v19, vcc
	v_add_f32_e32 v34, 1.0, v23
	v_add_f32_e32 v37, -1.0, v34
	v_frexp_mant_f32_e32 v38, v34
	v_cvt_f64_f32_e32 v[18:19], v34
	v_sub_f32_e32 v39, v37, v34
	v_frexp_exp_i32_f64_e32 v18, v[18:19]
	v_cmp_gt_f32_e32 vcc, s37, v38
	v_sub_f32_e32 v37, v23, v37
	v_add_f32_e32 v19, 1.0, v39
	v_subbrev_co_u32_e32 v18, vcc, 0, v18, vcc
	v_add_f32_e32 v19, v37, v19
	v_sub_u32_e32 v37, 0, v18
	v_cvt_f32_i32_e32 v18, v18
	v_ldexp_f32 v34, v34, v37
	v_ldexp_f32 v19, v19, v37
	v_add_f32_e32 v37, -1.0, v34
	v_add_f32_e32 v38, 1.0, v34
	v_add_f32_e32 v39, 1.0, v37
	v_add_f32_e32 v40, -1.0, v38
	v_sub_f32_e32 v39, v34, v39
	v_sub_f32_e32 v34, v34, v40
	v_mul_f32_e32 v40, 0x3f317218, v18
	v_add_f32_e32 v39, v19, v39
	v_add_f32_e32 v19, v19, v34
	v_fma_f32 v34, v18, s38, -v40
	v_add_f32_e32 v41, v37, v39
	v_add_f32_e32 v42, v38, v19
	v_fmac_f32_e32 v34, 0xb102e308, v18
	v_sub_f32_e32 v18, v37, v41
	v_sub_f32_e32 v37, v38, v42
	v_rcp_f32_e32 v38, v42
	v_add_f32_e32 v43, v40, v34
	v_add_f32_e32 v19, v19, v37
	v_sub_f32_e32 v37, v43, v40
	v_sub_f32_e32 v34, v34, v37
	v_mul_f32_e32 v37, v41, v38
	v_add_f32_e32 v18, v39, v18
	v_mul_f32_e32 v39, v42, v37
	v_fma_f32 v40, v37, v42, -v39
	v_fmac_f32_e32 v40, v37, v19
	v_add_f32_e32 v44, v39, v40
	v_sub_f32_e32 v45, v41, v44
	v_sub_f32_e32 v39, v44, v39
	v_sub_f32_e32 v41, v41, v45
	v_sub_f32_e32 v39, v39, v40
	v_sub_f32_e32 v40, v41, v44
	v_add_f32_e32 v18, v18, v40
	v_add_f32_e32 v18, v39, v18
	v_add_f32_e32 v39, v45, v18
	v_mul_f32_e32 v40, v38, v39
	v_sub_f32_e32 v41, v45, v39
	v_mul_f32_e32 v44, v42, v40
	v_add_f32_e32 v18, v18, v41
	v_add_f32_e32 v41, v37, v40
	v_fma_f32 v42, v40, v42, -v44
	v_sub_f32_e32 v37, v41, v37
	v_fmac_f32_e32 v42, v40, v19
	v_sub_f32_e32 v19, v40, v37
	v_add_f32_e32 v37, v44, v42
	v_sub_f32_e32 v40, v37, v44
	v_sub_f32_e32 v44, v39, v37
	v_sub_f32_e32 v39, v39, v44
	v_sub_f32_e32 v37, v39, v37
	v_sub_f32_e32 v40, v40, v42
	v_add_f32_e32 v18, v18, v37
	v_add_f32_e32 v18, v40, v18
	v_add_f32_e32 v18, v44, v18
	v_mul_f32_e32 v18, v38, v18
	v_add_f32_e32 v18, v19, v18
	v_add_f32_e32 v19, v41, v18
	v_mul_f32_e32 v37, v19, v19
	v_fmamk_f32 v40, v37, 0x3e9b6dac, v31
	v_sub_f32_e32 v38, v19, v41
	v_ldexp_f32 v39, v19, 1
	v_mul_f32_e32 v19, v19, v37
	v_fmaak_f32 v37, v37, v40, 0x3f2aaada
	v_mul_f32_e32 v19, v19, v37
	v_add_f32_e32 v37, v39, v19
	v_sub_f32_e32 v18, v18, v38
	v_sub_f32_e32 v38, v37, v39
	v_ldexp_f32 v18, v18, 1
	v_sub_f32_e32 v19, v19, v38
	v_add_f32_e32 v18, v18, v19
	v_add_f32_e32 v19, v37, v18
	v_sub_f32_e32 v37, v19, v37
	v_add_f32_e32 v38, v43, v19
	v_sub_f32_e32 v18, v18, v37
	v_sub_f32_e32 v37, v38, v43
	v_sub_f32_e32 v39, v38, v37
	v_sub_f32_e32 v19, v19, v37
	v_add_f32_e32 v37, v34, v18
	v_sub_f32_e32 v39, v43, v39
	v_sub_f32_e32 v40, v37, v34
	v_add_f32_e32 v19, v19, v39
	v_sub_f32_e32 v39, v37, v40
	v_sub_f32_e32 v18, v18, v40
	v_sub_f32_e32 v34, v34, v39
	v_add_f32_e32 v19, v37, v19
	v_add_f32_e32 v18, v18, v34
	v_add_f32_e32 v34, v38, v19
	v_sub_f32_e32 v37, v34, v38
	v_sub_f32_e32 v19, v19, v37
	v_add_f32_e32 v18, v18, v19
	v_add_f32_e32 v18, v34, v18
	v_cmp_neq_f32_e32 vcc, s36, v23
	s_nop 1
	v_cndmask_b32_e32 v18, v33, v18, vcc
	v_cmp_lt_f32_e64 vcc, |v23|, s39
	s_nop 1
	v_cndmask_b32_e32 v18, v18, v23, vcc
	v_mul_f32_e32 v18, v22, v18
	v_add_f32_e32 v19, v18, v18
	v_mul_f32_e32 v19, 0x3fb8aa3b, v19
	v_exp_f32_e32 v19, v19
	v_mul_f32_e32 v18, 0x3fb8aa3b, v18
	v_exp_f32_e32 v18, v18
	v_sub_f32_e32 v19, 1.0, v19
	v_max_f32_e32 v19, 0, v19
	v_mul_f32_e32 v22, 0x4f800000, v19
	v_cmp_gt_f32_e32 vcc, s40, v19
	s_nop 1
	v_cndmask_b32_e32 v19, v19, v22, vcc
	v_sqrt_f32_e32 v22, v19
	s_nop 0
	v_add_u32_e32 v23, -1, v22
	v_add_u32_e32 v34, 1, v22
	v_fma_f32 v37, -v23, v22, v19
	v_fma_f32 v38, -v34, v22, v19
	v_cmp_ge_f32_e64 s[0:1], 0, v37
	s_nop 1
	v_cndmask_b32_e64 v22, v22, v23, s[0:1]
	v_cmp_lt_f32_e64 s[0:1], 0, v38
	s_nop 1
	v_cndmask_b32_e64 v22, v22, v34, s[0:1]
	v_mul_f32_e32 v23, 0x37800000, v22
	v_cndmask_b32_e32 v22, v22, v23, vcc
	v_cmp_class_f32_e32 vcc, v19, v32
	s_lshl_b32 s0, s50, 2
	s_nop 0
	v_cndmask_b32_e32 v19, v22, v19, vcc
	v_mul_f32_e32 v19, v21, v19
	v_mul_f32_e32 v34, v1, v19
	s_waitcnt vmcnt(4)
	v_fmac_f32_e32 v34, v20, v18
	v_lshl_add_u64 v[18:19], s[20:21], 0, v[2:3]
	v_add_co_u32_e32 v18, vcc, s41, v18
	s_waitcnt vmcnt(0)
	v_lshlrev_b32_e32 v2, 16, v36
	v_addc_co_u32_e32 v19, vcc, 0, v19, vcc
	global_store_dword v[18:19], v34, off
	v_or_b32_e32 v18, s18, v0
	v_ashrrev_i32_e32 v19, 31, v18
	v_lshlrev_b64 v[18:19], 10, v[18:19]
	v_lshl_add_u64 v[18:19], s[56:57], 0, v[18:19]
	v_lshl_add_u64 v[18:19], v[18:19], 0, s[2:3]
	ds_write_b32 v13, v2
	s_waitcnt lgkmcnt(0)
	v_lshlrev_b32_e32 v1, 16, v80
	v_and_b32_e32 v21, 15, v0
	v_lshrrev_b32_e32 v22, 4, v0
	v_lshl_add_u32 v113, v22, 2, v126
	v_lshlrev_b32_e32 v23, 4, v22
	v_sub_u32_e32 v23, v23, v22
	v_add_u32_e32 v23, v23, v21
	v_lshlrev_b32_e32 v23, 10, v23
	v_lshlrev_b32_e32 v112, 4, v21
	v_sub_u32_e32 v22, v112, v23
	v_add_u32_e32 v22, 0x1000, v22
	v_add_u32_e32 v112, v126, v112
	v_ashrrev_i32_e32 v23, 31, v22
	ds_read_b128 v[116:119], v112
	v_mov_b32_e32 v114, 0x2000
	v_mov_b32_e32 v115, 0
	v_lshl_add_u64 v[22:23], v[18:19], 0, v[22:23]
	global_load_dwordx4 v[36:39], v[22:23], off offset:-4096
	global_load_dwordx4 v[40:43], v[22:23], off
	v_lshl_add_u64 v[22:23], v[22:23], 0, v[114:115]
	global_load_dwordx4 v[44:47], v[22:23], off offset:-4096
	global_load_dwordx4 v[48:51], v[22:23], off
	v_lshl_add_u64 v[22:23], v[22:23], 0, v[114:115]
	global_load_dwordx4 v[52:55], v[22:23], off offset:-4096
	global_load_dwordx4 v[56:59], v[22:23], off
	v_lshl_add_u64 v[22:23], v[22:23], 0, v[114:115]
	global_load_dwordx4 v[60:63], v[22:23], off offset:-4096
	global_load_dwordx4 v[64:67], v[22:23], off
	v_lshl_add_u64 v[22:23], v[22:23], 0, v[114:115]
	global_load_dwordx4 v[68:71], v[22:23], off offset:-4096
	global_load_dwordx4 v[72:75], v[22:23], off
	v_lshl_add_u64 v[22:23], v[22:23], 0, v[114:115]
	global_load_dwordx4 v[76:79], v[22:23], off offset:-4096
	global_load_dwordx4 v[80:83], v[22:23], off
	v_lshl_add_u64 v[22:23], v[22:23], 0, v[114:115]
	global_load_dwordx4 v[84:87], v[22:23], off offset:-4096
	global_load_dwordx4 v[88:91], v[22:23], off
	v_lshl_add_u64 v[22:23], v[22:23], 0, v[114:115]
	global_load_dwordx4 v[92:95], v[22:23], off offset:-4096
	global_load_dwordx4 v[96:99], v[22:23], off
	v_lshl_add_u64 v[22:23], v[22:23], 0, v[114:115]
	s_waitcnt vmcnt(12) lgkmcnt(0)
	v_mul_f32_e32 v100, v36, v116
	v_mul_f32_e32 v101, v40, v116
	v_mul_f32_e32 v102, v44, v116
	v_mul_f32_e32 v103, v48, v116
	v_fmac_f32_e32 v100, v37, v117
	v_fmac_f32_e32 v101, v41, v117
	v_fmac_f32_e32 v102, v45, v117
	v_fmac_f32_e32 v103, v49, v117
	v_fmac_f32_e32 v100, v38, v118
	v_fmac_f32_e32 v101, v42, v118
	v_fmac_f32_e32 v102, v46, v118
	v_fmac_f32_e32 v103, v50, v118
	v_fmac_f32_e32 v100, v39, v119
	v_fmac_f32_e32 v101, v43, v119
	v_fmac_f32_e32 v102, v47, v119
	v_fmac_f32_e32 v103, v51, v119
	global_load_dwordx4 v[36:39], v[22:23], off offset:-4096
	global_load_dwordx4 v[40:43], v[22:23], off
	v_lshl_add_u64 v[22:23], v[22:23], 0, v[114:115]
	global_load_dwordx4 v[44:47], v[22:23], off offset:-4096
	global_load_dwordx4 v[48:51], v[22:23], off
	v_lshl_add_u64 v[22:23], v[22:23], 0, v[114:115]
	v_add_f32_dpp v100, v100, v100 row_ror:8 row_mask:0xf bank_mask:0xf
	v_add_f32_dpp v101, v101, v101 row_ror:8 row_mask:0xf bank_mask:0xf
	v_add_f32_dpp v102, v102, v102 row_ror:8 row_mask:0xf bank_mask:0xf
	v_add_f32_dpp v103, v103, v103 row_ror:8 row_mask:0xf bank_mask:0xf
	v_add_f32_dpp v100, v100, v100 row_ror:4 row_mask:0xf bank_mask:0xf
	v_add_f32_dpp v101, v101, v101 row_ror:4 row_mask:0xf bank_mask:0xf
	v_add_f32_dpp v102, v102, v102 row_ror:4 row_mask:0xf bank_mask:0xf
	v_add_f32_dpp v103, v103, v103 row_ror:4 row_mask:0xf bank_mask:0xf
	v_add_f32_dpp v100, v100, v100 row_ror:2 row_mask:0xf bank_mask:0xf
	v_add_f32_dpp v101, v101, v101 row_ror:2 row_mask:0xf bank_mask:0xf
	v_add_f32_dpp v102, v102, v102 row_ror:2 row_mask:0xf bank_mask:0xf
	v_add_f32_dpp v103, v103, v103 row_ror:2 row_mask:0xf bank_mask:0xf
	v_add_f32_dpp v100, v100, v100 row_ror:1 row_mask:0xf bank_mask:0xf
	v_add_f32_dpp v101, v101, v101 row_ror:1 row_mask:0xf bank_mask:0xf
	v_add_f32_dpp v102, v102, v102 row_ror:1 row_mask:0xf bank_mask:0xf
	v_add_f32_dpp v103, v103, v103 row_ror:1 row_mask:0xf bank_mask:0xf
	s_nop 1
	ds_write_b32 v113, v100 offset:256
	ds_write_b32 v113, v101 offset:272
	ds_write_b32 v113, v102 offset:288
	ds_write_b32 v113, v103 offset:304
	s_waitcnt vmcnt(12)
	v_mul_f32_e32 v104, v52, v116
	v_mul_f32_e32 v105, v56, v116
	v_mul_f32_e32 v106, v60, v116
	v_mul_f32_e32 v107, v64, v116
	v_fmac_f32_e32 v104, v53, v117
	v_fmac_f32_e32 v105, v57, v117
	v_fmac_f32_e32 v106, v61, v117
	v_fmac_f32_e32 v107, v65, v117
	v_fmac_f32_e32 v104, v54, v118
	v_fmac_f32_e32 v105, v58, v118
	v_fmac_f32_e32 v106, v62, v118
	v_fmac_f32_e32 v107, v66, v118
	v_fmac_f32_e32 v104, v55, v119
	v_fmac_f32_e32 v105, v59, v119
	v_fmac_f32_e32 v106, v63, v119
	v_fmac_f32_e32 v107, v67, v119
	global_load_dwordx4 v[52:55], v[22:23], off offset:-4096
	global_load_dwordx4 v[56:59], v[22:23], off
	v_lshl_add_u64 v[22:23], v[22:23], 0, v[114:115]
	global_load_dwordx4 v[60:63], v[22:23], off offset:-4096
	global_load_dwordx4 v[64:67], v[22:23], off
	v_lshl_add_u64 v[22:23], v[22:23], 0, v[114:115]
	v_add_f32_dpp v104, v104, v104 row_ror:8 row_mask:0xf bank_mask:0xf
	v_add_f32_dpp v105, v105, v105 row_ror:8 row_mask:0xf bank_mask:0xf
	v_add_f32_dpp v106, v106, v106 row_ror:8 row_mask:0xf bank_mask:0xf
	v_add_f32_dpp v107, v107, v107 row_ror:8 row_mask:0xf bank_mask:0xf
	v_add_f32_dpp v104, v104, v104 row_ror:4 row_mask:0xf bank_mask:0xf
	v_add_f32_dpp v105, v105, v105 row_ror:4 row_mask:0xf bank_mask:0xf
	v_add_f32_dpp v106, v106, v106 row_ror:4 row_mask:0xf bank_mask:0xf
	v_add_f32_dpp v107, v107, v107 row_ror:4 row_mask:0xf bank_mask:0xf
	v_add_f32_dpp v104, v104, v104 row_ror:2 row_mask:0xf bank_mask:0xf
	v_add_f32_dpp v105, v105, v105 row_ror:2 row_mask:0xf bank_mask:0xf
	v_add_f32_dpp v106, v106, v106 row_ror:2 row_mask:0xf bank_mask:0xf
	v_add_f32_dpp v107, v107, v107 row_ror:2 row_mask:0xf bank_mask:0xf
	v_add_f32_dpp v104, v104, v104 row_ror:1 row_mask:0xf bank_mask:0xf
	v_add_f32_dpp v105, v105, v105 row_ror:1 row_mask:0xf bank_mask:0xf
	v_add_f32_dpp v106, v106, v106 row_ror:1 row_mask:0xf bank_mask:0xf
	v_add_f32_dpp v107, v107, v107 row_ror:1 row_mask:0xf bank_mask:0xf
	s_nop 1
	ds_write_b32 v113, v104 offset:320
	ds_write_b32 v113, v105 offset:336
	ds_write_b32 v113, v106 offset:352
	ds_write_b32 v113, v107 offset:368
	s_waitcnt vmcnt(12)
	v_mul_f32_e32 v100, v68, v116
	v_mul_f32_e32 v101, v72, v116
	v_mul_f32_e32 v102, v76, v116
	v_mul_f32_e32 v103, v80, v116
	v_fmac_f32_e32 v100, v69, v117
	v_fmac_f32_e32 v101, v73, v117
	v_fmac_f32_e32 v102, v77, v117
	v_fmac_f32_e32 v103, v81, v117
	v_fmac_f32_e32 v100, v70, v118
	v_fmac_f32_e32 v101, v74, v118
	v_fmac_f32_e32 v102, v78, v118
	v_fmac_f32_e32 v103, v82, v118
	v_fmac_f32_e32 v100, v71, v119
	v_fmac_f32_e32 v101, v75, v119
	v_fmac_f32_e32 v102, v79, v119
	v_fmac_f32_e32 v103, v83, v119
	global_load_dwordx4 v[68:71], v[22:23], off offset:-4096
	global_load_dwordx4 v[72:75], v[22:23], off
	v_lshl_add_u64 v[22:23], v[22:23], 0, v[114:115]
	global_load_dwordx4 v[76:79], v[22:23], off offset:-4096
	global_load_dwordx4 v[80:83], v[22:23], off
	v_lshl_add_u64 v[22:23], v[22:23], 0, v[114:115]
	v_add_f32_dpp v100, v100, v100 row_ror:8 row_mask:0xf bank_mask:0xf
	v_add_f32_dpp v101, v101, v101 row_ror:8 row_mask:0xf bank_mask:0xf
	v_add_f32_dpp v102, v102, v102 row_ror:8 row_mask:0xf bank_mask:0xf
	v_add_f32_dpp v103, v103, v103 row_ror:8 row_mask:0xf bank_mask:0xf
	v_add_f32_dpp v100, v100, v100 row_ror:4 row_mask:0xf bank_mask:0xf
	v_add_f32_dpp v101, v101, v101 row_ror:4 row_mask:0xf bank_mask:0xf
	v_add_f32_dpp v102, v102, v102 row_ror:4 row_mask:0xf bank_mask:0xf
	v_add_f32_dpp v103, v103, v103 row_ror:4 row_mask:0xf bank_mask:0xf
	v_add_f32_dpp v100, v100, v100 row_ror:2 row_mask:0xf bank_mask:0xf
	v_add_f32_dpp v101, v101, v101 row_ror:2 row_mask:0xf bank_mask:0xf
	v_add_f32_dpp v102, v102, v102 row_ror:2 row_mask:0xf bank_mask:0xf
	v_add_f32_dpp v103, v103, v103 row_ror:2 row_mask:0xf bank_mask:0xf
	v_add_f32_dpp v100, v100, v100 row_ror:1 row_mask:0xf bank_mask:0xf
	v_add_f32_dpp v101, v101, v101 row_ror:1 row_mask:0xf bank_mask:0xf
	v_add_f32_dpp v102, v102, v102 row_ror:1 row_mask:0xf bank_mask:0xf
	v_add_f32_dpp v103, v103, v103 row_ror:1 row_mask:0xf bank_mask:0xf
	s_nop 1
	ds_write_b32 v113, v100 offset:384
	ds_write_b32 v113, v101 offset:400
	ds_write_b32 v113, v102 offset:416
	ds_write_b32 v113, v103 offset:432
	s_waitcnt vmcnt(12)
	v_mul_f32_e32 v104, v84, v116
	v_mul_f32_e32 v105, v88, v116
	v_mul_f32_e32 v106, v92, v116
	v_mul_f32_e32 v107, v96, v116
	v_fmac_f32_e32 v104, v85, v117
	v_fmac_f32_e32 v105, v89, v117
	v_fmac_f32_e32 v106, v93, v117
	v_fmac_f32_e32 v107, v97, v117
	v_fmac_f32_e32 v104, v86, v118
	v_fmac_f32_e32 v105, v90, v118
	v_fmac_f32_e32 v106, v94, v118
	v_fmac_f32_e32 v107, v98, v118
	v_fmac_f32_e32 v104, v87, v119
	v_fmac_f32_e32 v105, v91, v119
	v_fmac_f32_e32 v106, v95, v119
	v_fmac_f32_e32 v107, v99, v119
	global_load_dwordx4 v[84:87], v[22:23], off offset:-4096
	global_load_dwordx4 v[88:91], v[22:23], off
	v_lshl_add_u64 v[22:23], v[22:23], 0, v[114:115]
	global_load_dwordx4 v[92:95], v[22:23], off offset:-4096
	global_load_dwordx4 v[96:99], v[22:23], off
	v_mov_b32_e32 v20, s0
	global_load_dword v20, v20, s[84:85]
	v_add_f32_dpp v104, v104, v104 row_ror:8 row_mask:0xf bank_mask:0xf
	v_add_f32_dpp v105, v105, v105 row_ror:8 row_mask:0xf bank_mask:0xf
	v_add_f32_dpp v106, v106, v106 row_ror:8 row_mask:0xf bank_mask:0xf
	v_add_f32_dpp v107, v107, v107 row_ror:8 row_mask:0xf bank_mask:0xf
	v_add_f32_dpp v104, v104, v104 row_ror:4 row_mask:0xf bank_mask:0xf
	v_add_f32_dpp v105, v105, v105 row_ror:4 row_mask:0xf bank_mask:0xf
	v_add_f32_dpp v106, v106, v106 row_ror:4 row_mask:0xf bank_mask:0xf
	v_add_f32_dpp v107, v107, v107 row_ror:4 row_mask:0xf bank_mask:0xf
	v_add_f32_dpp v104, v104, v104 row_ror:2 row_mask:0xf bank_mask:0xf
	v_add_f32_dpp v105, v105, v105 row_ror:2 row_mask:0xf bank_mask:0xf
	v_add_f32_dpp v106, v106, v106 row_ror:2 row_mask:0xf bank_mask:0xf
	v_add_f32_dpp v107, v107, v107 row_ror:2 row_mask:0xf bank_mask:0xf
	v_add_f32_dpp v104, v104, v104 row_ror:1 row_mask:0xf bank_mask:0xf
	v_add_f32_dpp v105, v105, v105 row_ror:1 row_mask:0xf bank_mask:0xf
	v_add_f32_dpp v106, v106, v106 row_ror:1 row_mask:0xf bank_mask:0xf
	v_add_f32_dpp v107, v107, v107 row_ror:1 row_mask:0xf bank_mask:0xf
	s_nop 1
	ds_write_b32 v113, v104 offset:448
	ds_write_b32 v113, v105 offset:464
	ds_write_b32 v113, v106 offset:480
	ds_write_b32 v113, v107 offset:496
	s_waitcnt vmcnt(13)
	v_mul_f32_e32 v100, v36, v116
	v_mul_f32_e32 v101, v40, v116
	v_mul_f32_e32 v102, v44, v116
	v_mul_f32_e32 v103, v48, v116
	v_fmac_f32_e32 v100, v37, v117
	v_fmac_f32_e32 v101, v41, v117
	v_fmac_f32_e32 v102, v45, v117
	v_fmac_f32_e32 v103, v49, v117
	v_fmac_f32_e32 v100, v38, v118
	v_fmac_f32_e32 v101, v42, v118
	v_fmac_f32_e32 v102, v46, v118
	v_fmac_f32_e32 v103, v50, v118
	v_fmac_f32_e32 v100, v39, v119
	v_fmac_f32_e32 v101, v43, v119
	v_fmac_f32_e32 v102, v47, v119
	v_fmac_f32_e32 v103, v51, v119
	v_add_f32_dpp v100, v100, v100 row_ror:8 row_mask:0xf bank_mask:0xf
	v_add_f32_dpp v101, v101, v101 row_ror:8 row_mask:0xf bank_mask:0xf
	v_add_f32_dpp v102, v102, v102 row_ror:8 row_mask:0xf bank_mask:0xf
	v_add_f32_dpp v103, v103, v103 row_ror:8 row_mask:0xf bank_mask:0xf
	v_add_f32_dpp v100, v100, v100 row_ror:4 row_mask:0xf bank_mask:0xf
	v_add_f32_dpp v101, v101, v101 row_ror:4 row_mask:0xf bank_mask:0xf
	v_add_f32_dpp v102, v102, v102 row_ror:4 row_mask:0xf bank_mask:0xf
	v_add_f32_dpp v103, v103, v103 row_ror:4 row_mask:0xf bank_mask:0xf
	v_add_f32_dpp v100, v100, v100 row_ror:2 row_mask:0xf bank_mask:0xf
	v_add_f32_dpp v101, v101, v101 row_ror:2 row_mask:0xf bank_mask:0xf
	v_add_f32_dpp v102, v102, v102 row_ror:2 row_mask:0xf bank_mask:0xf
	v_add_f32_dpp v103, v103, v103 row_ror:2 row_mask:0xf bank_mask:0xf
	v_add_f32_dpp v100, v100, v100 row_ror:1 row_mask:0xf bank_mask:0xf
	v_add_f32_dpp v101, v101, v101 row_ror:1 row_mask:0xf bank_mask:0xf
	v_add_f32_dpp v102, v102, v102 row_ror:1 row_mask:0xf bank_mask:0xf
	v_add_f32_dpp v103, v103, v103 row_ror:1 row_mask:0xf bank_mask:0xf
	s_nop 1
	ds_write_b32 v113, v100 offset:512
	ds_write_b32 v113, v101 offset:528
	ds_write_b32 v113, v102 offset:544
	ds_write_b32 v113, v103 offset:560
	s_waitcnt vmcnt(9)
	v_mul_f32_e32 v104, v52, v116
	v_mul_f32_e32 v105, v56, v116
	v_mul_f32_e32 v106, v60, v116
	v_mul_f32_e32 v107, v64, v116
	v_fmac_f32_e32 v104, v53, v117
	v_fmac_f32_e32 v105, v57, v117
	v_fmac_f32_e32 v106, v61, v117
	v_fmac_f32_e32 v107, v65, v117
	v_fmac_f32_e32 v104, v54, v118
	v_fmac_f32_e32 v105, v58, v118
	v_fmac_f32_e32 v106, v62, v118
	v_fmac_f32_e32 v107, v66, v118
	v_fmac_f32_e32 v104, v55, v119
	v_fmac_f32_e32 v105, v59, v119
	v_fmac_f32_e32 v106, v63, v119
	v_fmac_f32_e32 v107, v67, v119
	v_add_f32_dpp v104, v104, v104 row_ror:8 row_mask:0xf bank_mask:0xf
	v_add_f32_dpp v105, v105, v105 row_ror:8 row_mask:0xf bank_mask:0xf
	v_add_f32_dpp v106, v106, v106 row_ror:8 row_mask:0xf bank_mask:0xf
	v_add_f32_dpp v107, v107, v107 row_ror:8 row_mask:0xf bank_mask:0xf
	v_add_f32_dpp v104, v104, v104 row_ror:4 row_mask:0xf bank_mask:0xf
	v_add_f32_dpp v105, v105, v105 row_ror:4 row_mask:0xf bank_mask:0xf
	v_add_f32_dpp v106, v106, v106 row_ror:4 row_mask:0xf bank_mask:0xf
	v_add_f32_dpp v107, v107, v107 row_ror:4 row_mask:0xf bank_mask:0xf
	v_add_f32_dpp v104, v104, v104 row_ror:2 row_mask:0xf bank_mask:0xf
	v_add_f32_dpp v105, v105, v105 row_ror:2 row_mask:0xf bank_mask:0xf
	v_add_f32_dpp v106, v106, v106 row_ror:2 row_mask:0xf bank_mask:0xf
	v_add_f32_dpp v107, v107, v107 row_ror:2 row_mask:0xf bank_mask:0xf
	v_add_f32_dpp v104, v104, v104 row_ror:1 row_mask:0xf bank_mask:0xf
	v_add_f32_dpp v105, v105, v105 row_ror:1 row_mask:0xf bank_mask:0xf
	v_add_f32_dpp v106, v106, v106 row_ror:1 row_mask:0xf bank_mask:0xf
	v_add_f32_dpp v107, v107, v107 row_ror:1 row_mask:0xf bank_mask:0xf
	s_nop 1
	ds_write_b32 v113, v104 offset:576
	ds_write_b32 v113, v105 offset:592
	ds_write_b32 v113, v106 offset:608
	ds_write_b32 v113, v107 offset:624
	s_waitcnt vmcnt(5)
	v_mul_f32_e32 v100, v68, v116
	v_mul_f32_e32 v101, v72, v116
	v_mul_f32_e32 v102, v76, v116
	v_mul_f32_e32 v103, v80, v116
	v_fmac_f32_e32 v100, v69, v117
	v_fmac_f32_e32 v101, v73, v117
	v_fmac_f32_e32 v102, v77, v117
	v_fmac_f32_e32 v103, v81, v117
	v_fmac_f32_e32 v100, v70, v118
	v_fmac_f32_e32 v101, v74, v118
	v_fmac_f32_e32 v102, v78, v118
	v_fmac_f32_e32 v103, v82, v118
	v_fmac_f32_e32 v100, v71, v119
	v_fmac_f32_e32 v101, v75, v119
	v_fmac_f32_e32 v102, v79, v119
	v_fmac_f32_e32 v103, v83, v119
	v_add_f32_dpp v100, v100, v100 row_ror:8 row_mask:0xf bank_mask:0xf
	v_add_f32_dpp v101, v101, v101 row_ror:8 row_mask:0xf bank_mask:0xf
	v_add_f32_dpp v102, v102, v102 row_ror:8 row_mask:0xf bank_mask:0xf
	v_add_f32_dpp v103, v103, v103 row_ror:8 row_mask:0xf bank_mask:0xf
	v_add_f32_dpp v100, v100, v100 row_ror:4 row_mask:0xf bank_mask:0xf
	v_add_f32_dpp v101, v101, v101 row_ror:4 row_mask:0xf bank_mask:0xf
	v_add_f32_dpp v102, v102, v102 row_ror:4 row_mask:0xf bank_mask:0xf
	v_add_f32_dpp v103, v103, v103 row_ror:4 row_mask:0xf bank_mask:0xf
	v_add_f32_dpp v100, v100, v100 row_ror:2 row_mask:0xf bank_mask:0xf
	v_add_f32_dpp v101, v101, v101 row_ror:2 row_mask:0xf bank_mask:0xf
	v_add_f32_dpp v102, v102, v102 row_ror:2 row_mask:0xf bank_mask:0xf
	v_add_f32_dpp v103, v103, v103 row_ror:2 row_mask:0xf bank_mask:0xf
	v_add_f32_dpp v100, v100, v100 row_ror:1 row_mask:0xf bank_mask:0xf
	v_add_f32_dpp v101, v101, v101 row_ror:1 row_mask:0xf bank_mask:0xf
	v_add_f32_dpp v102, v102, v102 row_ror:1 row_mask:0xf bank_mask:0xf
	v_add_f32_dpp v103, v103, v103 row_ror:1 row_mask:0xf bank_mask:0xf
	s_nop 1
	ds_write_b32 v113, v100 offset:640
	ds_write_b32 v113, v101 offset:656
	ds_write_b32 v113, v102 offset:672
	ds_write_b32 v113, v103 offset:688
	s_waitcnt vmcnt(1)
	v_mul_f32_e32 v104, v84, v116
	v_mul_f32_e32 v105, v88, v116
	v_mul_f32_e32 v106, v92, v116
	v_mul_f32_e32 v107, v96, v116
	v_fmac_f32_e32 v104, v85, v117
	v_fmac_f32_e32 v105, v89, v117
	v_fmac_f32_e32 v106, v93, v117
	v_fmac_f32_e32 v107, v97, v117
	v_fmac_f32_e32 v104, v86, v118
	v_fmac_f32_e32 v105, v90, v118
	v_fmac_f32_e32 v106, v94, v118
	v_fmac_f32_e32 v107, v98, v118
	v_fmac_f32_e32 v104, v87, v119
	v_fmac_f32_e32 v105, v91, v119
	v_fmac_f32_e32 v106, v95, v119
	v_fmac_f32_e32 v107, v99, v119
	v_add_f32_dpp v104, v104, v104 row_ror:8 row_mask:0xf bank_mask:0xf
	v_add_f32_dpp v105, v105, v105 row_ror:8 row_mask:0xf bank_mask:0xf
	v_add_f32_dpp v106, v106, v106 row_ror:8 row_mask:0xf bank_mask:0xf
	v_add_f32_dpp v107, v107, v107 row_ror:8 row_mask:0xf bank_mask:0xf
	v_add_f32_dpp v104, v104, v104 row_ror:4 row_mask:0xf bank_mask:0xf
	v_add_f32_dpp v105, v105, v105 row_ror:4 row_mask:0xf bank_mask:0xf
	v_add_f32_dpp v106, v106, v106 row_ror:4 row_mask:0xf bank_mask:0xf
	v_add_f32_dpp v107, v107, v107 row_ror:4 row_mask:0xf bank_mask:0xf
	v_add_f32_dpp v104, v104, v104 row_ror:2 row_mask:0xf bank_mask:0xf
	v_add_f32_dpp v105, v105, v105 row_ror:2 row_mask:0xf bank_mask:0xf
	v_add_f32_dpp v106, v106, v106 row_ror:2 row_mask:0xf bank_mask:0xf
	v_add_f32_dpp v107, v107, v107 row_ror:2 row_mask:0xf bank_mask:0xf
	v_add_f32_dpp v104, v104, v104 row_ror:1 row_mask:0xf bank_mask:0xf
	v_add_f32_dpp v105, v105, v105 row_ror:1 row_mask:0xf bank_mask:0xf
	v_add_f32_dpp v106, v106, v106 row_ror:1 row_mask:0xf bank_mask:0xf
	v_add_f32_dpp v107, v107, v107 row_ror:1 row_mask:0xf bank_mask:0xf
	s_nop 1
	ds_write_b32 v113, v104 offset:704
	ds_write_b32 v113, v105 offset:720
	ds_write_b32 v113, v106 offset:736
	ds_write_b32 v113, v107 offset:752
	s_waitcnt lgkmcnt(0)
	ds_read_b32 v19, v13 offset:256
	ds_read_b32 v18, v13 offset:512
	s_waitcnt lgkmcnt(0)
	v_mul_f32_e32 v22, 0x3e000000, v19
	v_mul_f32_e32 v23, 0x3e000000, v18
	v_max_f32_e32 v22, v22, v23
	ds_bpermute_b32 v23, v24, v22
	v_mul_f32_e32 v21, v1, v2
	ds_bpermute_b32 v21, v24, v21
	s_lshl_b64 s[0:1], s[18:19], 10
	s_or_b32 s0, s0, s51
	s_waitcnt lgkmcnt(1)
	v_max_f32_e32 v23, v23, v23
	v_max_f32_e32 v22, v22, v23
	s_waitcnt lgkmcnt(0)
	v_fmac_f32_e32 v21, v1, v2
	ds_bpermute_b32 v23, v25, v22
	ds_bpermute_b32 v2, v25, v21
	s_movk_i32 s19, 0xfe00
	s_waitcnt lgkmcnt(1)
	v_max_f32_e32 v23, v23, v23
	s_waitcnt lgkmcnt(0)
	v_add_f32_e32 v2, v21, v2
	v_max_f32_e32 v22, v22, v23
	ds_bpermute_b32 v21, v26, v2
	ds_bpermute_b32 v23, v26, v22
	s_waitcnt lgkmcnt(1)
	v_add_f32_e32 v2, v2, v21
	s_waitcnt lgkmcnt(0)
	v_max_f32_e32 v23, v23, v23
	ds_bpermute_b32 v21, v27, v2
	v_max_f32_e32 v22, v22, v23
	ds_bpermute_b32 v23, v27, v22
	s_waitcnt lgkmcnt(1)
	v_add_f32_e32 v2, v2, v21
	ds_bpermute_b32 v21, v28, v2
	s_waitcnt lgkmcnt(1)
	v_max_f32_e32 v23, v23, v23
	v_max_f32_e32 v22, v22, v23
	ds_bpermute_b32 v23, v28, v22
	s_waitcnt lgkmcnt(1)
	v_add_f32_e32 v2, v2, v21
	ds_bpermute_b32 v21, v29, v2
	s_waitcnt vmcnt(0)
	v_max_f32_e32 v36, v20, v20
	s_waitcnt lgkmcnt(1)
	v_max_f32_e32 v23, v23, v23
	v_max_f32_e32 v22, v22, v23
	ds_bpermute_b32 v23, v29, v22
	s_waitcnt lgkmcnt(1)
	v_add_f32_e32 v21, v2, v21
	v_mul_f32_e32 v2, 0x3e000000, v21
	v_max_f32_e32 v2, v2, v36
	s_waitcnt lgkmcnt(0)
	v_max3_f32 v22, v22, v23, v2
	v_fma_f32 v2, v19, s43, -v22
	v_mul_f32_e32 v2, 0x3fb8aa3b, v2
	v_exp_f32_e32 v19, v2
	v_fma_f32 v2, v18, s43, -v22
	v_mul_f32_e32 v2, 0x3fb8aa3b, v2
	v_exp_f32_e32 v18, v2
	v_fma_f32 v21, v21, s43, -v22
	v_mul_f32_e32 v21, 0x3fb8aa3b, v21
	v_add_f32_e32 v2, v19, v18
	ds_bpermute_b32 v23, v24, v2
	ds_write2st64_b32 v13, v19, v18 offset0:1 offset1:2
	s_waitcnt lgkmcnt(0)
	v_lshl_add_u64 v[18:19], v[8:9], 0, s[0:1]
	s_waitcnt lgkmcnt(1)
	v_add_f32_e32 v2, v2, v23
	ds_bpermute_b32 v23, v25, v2
	s_waitcnt lgkmcnt(0)
	v_add_f32_e32 v2, v2, v23
	ds_bpermute_b32 v23, v26, v2
	s_waitcnt lgkmcnt(0)
	v_add_f32_e32 v2, v2, v23
	ds_bpermute_b32 v23, v27, v2
	s_waitcnt lgkmcnt(0)
	v_add_f32_e32 v36, v2, v23
	ds_bpermute_b32 v37, v28, v36
	v_lshlrev_b32_e32 v2, 16, v35
	v_exp_f32_e32 v23, v21
	s_waitcnt lgkmcnt(0)
	v_add_f32_e32 v35, v36, v37
	ds_bpermute_b32 v36, v29, v35
	v_mul_f32_e32 v21, v23, v2
